# conv+HGRN phase reordered (HGRN2 chunk units first, conv rows second) behind a split seam: wait only for the aggregate producers (write-through stores + counter), check the grid round before the conv
# speedup vs baseline: 1.0052x; 1.0052x over previous
; __device__ __forceinline__ void hg_a2_quad(unsigned char* ws, float* Gp, LAS unsigned char* lds, int quad, int tid) {
;     ...
;     float* tp = Gp + (size_t)(256 + quad) * 16384 + (size_t)(wave * 8) * 256 + lane * 4;
; #pragma unroll
;     for (int kt = 0; kt < 8; ++kt) *(f32x4*)(tp + kt * 256) = R[kt];
.LBB0_576:
	s_ashr_i32 s17, s16, 31
	s_lshl_b64 s[22:23], s[16:17], 16
	v_lshl_add_u64 v[36:37], v[34:35], 0, s[22:23]
	v_add_co_u32_e32 v40, vcc, 0x1000000, v36
	v_lshl_add_u64 v[38:39], v[36:37], 0, s[20:21]
	s_nop 0
	v_addc_co_u32_e32 v41, vcc, 0, v37, vcc
	global_store_dwordx4 v[40:41], v[28:31], off sc1
	global_store_dwordx4 v[38:39], v[24:27], off offset:1024 sc1
	global_store_dwordx4 v[38:39], v[16:19], off offset:2048 sc1
	global_store_dwordx4 v[38:39], v[20:23], off offset:3072 sc1
	s_add_i32 s16, s26, s16
	v_add_co_u32_e32 v16, vcc, 0x1001000, v36
	s_add_i32 s28, s28, s29
	s_add_i32 s30, s30, s31
	v_addc_co_u32_e32 v17, vcc, 0, v37, vcc
	s_cmp_lt_i32 s16, 64
	v_add_u32_e32 v52, s27, v52
	global_store_dwordx4 v[16:17], v[8:11], off sc1
	global_store_dwordx4 v[16:17], v[4:7], off offset:1024 sc1
	global_store_dwordx4 v[16:17], v[0:3], off offset:2048 sc1
	global_store_dwordx4 v[16:17], v[12:15], off offset:3072 sc1
	s_cbranch_scc0 .LBB0_583

; __device__ __forceinline__ void hg_a2_quad(unsigned char* ws, float* Gp, LAS unsigned char* lds, int quad, int tid) {
;     ...
;         const size_t gofs = (size_t)(row0 + seg * 64) * 512 + h * 128 + k;
;         const _Float16* lfp = (const _Float16*)(ws + WS_LF) + gofs; const bf16* vp = (const bf16*)(ws + WS_VV) + gofs;
;         float lf[64]; unsigned vq[32];
; #pragma unroll
;         for (int i = 0; i < 64; ++i) lf[i] = (float)lfp[(size_t)i * 512];
; #pragma unroll
;         for (int i = 0; i < 32; ++i) vq[i] = (unsigned)vp[(size_t)(2 * i) * 512] | ((unsigned)vp[(size_t)(2 * i + 1) * 512] << 16);
.LBB0_579:
	s_and_b32 s22, s17, 0xf00
	v_add_u32_e32 v38, s22, v55
	v_ashrrev_i32_e32 v39, 31, v38
	v_lshlrev_b64 v[86:87], 10, v[38:39]
	v_lshl_or_b32 v86, v32, 1, v86
	v_lshl_add_u64 v[88:89], s[10:11], 0, v[86:87]
	v_add_co_u32_e32 v64, vcc, s34, v88
	v_lshl_add_u64 v[86:87], s[12:13], 0, v[86:87]
	s_nop 0
	v_addc_co_u32_e32 v65, vcc, 0, v89, vcc
	v_add_co_u32_e32 v38, vcc, s35, v88
	s_cmp_eq_u32 s66, 0
	s_nop 0
	v_addc_co_u32_e32 v39, vcc, 0, v89, vcc
	v_add_co_u32_e32 v72, vcc, s36, v88
	s_nop 1
	v_addc_co_u32_e32 v73, vcc, 0, v89, vcc
	v_add_co_u32_e32 v40, vcc, s37, v88
	global_load_ushort v59, v[88:89], off
	global_load_ushort v60, v[88:89], off offset:1024
	global_load_ushort v61, v[88:89], off offset:2048
	global_load_ushort v62, v[88:89], off offset:3072
	global_load_ushort v56, v[64:65], off offset:1024
	global_load_ushort v57, v[64:65], off offset:2048
	global_load_ushort v58, v[64:65], off offset:3072
	global_load_ushort v37, v[72:73], off offset:1024
	v_addc_co_u32_e32 v41, vcc, 0, v89, vcc
	v_add_co_u32_e32 v80, vcc, s38, v88
	s_nop 1
	v_addc_co_u32_e32 v81, vcc, 0, v89, vcc
	v_add_co_u32_e32 v82, vcc, s39, v88
	s_nop 1
	v_addc_co_u32_e32 v83, vcc, 0, v89, vcc
	v_add_co_u32_e32 v84, vcc, s40, v88
	global_load_ushort v63, v[40:41], off
	global_load_ushort v64, v[40:41], off offset:1024
	global_load_ushort v65, v[40:41], off offset:2048
	global_load_ushort v66, v[40:41], off offset:3072
	global_load_ushort v67, v[82:83], off offset:-4096
	global_load_ushort v68, v[82:83], off
	global_load_ushort v69, v[82:83], off offset:1024
	global_load_ushort v70, v[82:83], off offset:2048
	v_addc_co_u32_e32 v85, vcc, 0, v89, vcc
	v_add_co_u32_e32 v90, vcc, s41, v88
	global_load_ushort v77, v[72:73], off offset:2048
	global_load_ushort v78, v[72:73], off offset:3072
	global_load_ushort v74, v[80:81], off offset:1024
	global_load_ushort v75, v[80:81], off offset:2048
	global_load_ushort v76, v[80:81], off offset:3072
	global_load_ushort v71, v[84:85], off offset:1024
	s_nop 0
	global_load_ushort v72, v[84:85], off offset:2048
	global_load_ushort v73, v[84:85], off offset:3072
	v_addc_co_u32_e32 v91, vcc, 0, v89, vcc
	v_add_co_u32_e32 v102, vcc, s42, v88
	s_nop 1
	v_addc_co_u32_e32 v103, vcc, 0, v89, vcc
	v_add_co_u32_e32 v96, vcc, s43, v88
	s_nop 1
	v_addc_co_u32_e32 v97, vcc, 0, v89, vcc
	global_load_ushort v83, v[82:83], off offset:3072
	s_nop 0
	global_load_ushort v84, v[90:91], off offset:-4096
	global_load_ushort v79, v[90:91], off
	global_load_ushort v80, v[90:91], off offset:1024
	global_load_ushort v81, v[90:91], off offset:2048
	global_load_ushort v82, v[90:91], off offset:3072
	global_load_ushort v92, v[96:97], off offset:-4096
	global_load_ushort v93, v[96:97], off
	v_add_co_u32_e32 v90, vcc, s61, v88
	s_nop 1
	v_addc_co_u32_e32 v91, vcc, 0, v89, vcc
	v_add_co_u32_e32 v104, vcc, s62, v88
	s_nop 1
	v_addc_co_u32_e32 v105, vcc, 0, v89, vcc
	v_add_co_u32_e32 v110, vcc, s63, v88
	global_load_ushort v94, v[96:97], off offset:1024
	global_load_ushort v95, v[96:97], off offset:2048
	s_nop 0
	global_load_ushort v96, v[96:97], off offset:3072
	s_nop 0
	global_load_ushort v97, v[104:105], off offset:-4096
	global_load_ushort v98, v[104:105], off
	global_load_ushort v99, v[104:105], off offset:1024
	global_load_ushort v100, v[104:105], off offset:2048
	global_load_ushort v101, v[104:105], off offset:3072
	v_addc_co_u32_e32 v111, vcc, 0, v89, vcc
	v_add_co_u32_e32 v118, vcc, s64, v88
	global_load_ushort v107, v[102:103], off offset:1024
	global_load_ushort v108, v[102:103], off offset:2048
	global_load_ushort v109, v[102:103], off offset:3072
	global_load_ushort v104, v[90:91], off offset:1024
	global_load_ushort v105, v[90:91], off offset:2048
	global_load_ushort v106, v[90:91], off offset:3072
	s_nop 0
	global_load_ushort v102, v[110:111], off offset:1024
	global_load_ushort v103, v[110:111], off offset:2048
	v_addc_co_u32_e32 v119, vcc, 0, v89, vcc
	v_add_co_u32_e32 v88, vcc, s65, v88
	s_nop 1
	v_addc_co_u32_e32 v89, vcc, 0, v89, vcc
	global_load_ushort v117, v[110:111], off offset:3072
	global_load_ushort v112, v[88:89], off
	global_load_ushort v113, v[88:89], off offset:1024
	global_load_ushort v114, v[88:89], off offset:2048
	global_load_ushort v115, v[88:89], off offset:3072
	s_nop 0
	global_load_ushort v110, v[86:87], off
	global_load_ushort v116, v[86:87], off offset:1024
	global_load_ushort v111, v[86:87], off offset:2048
	v_add_co_u32_e32 v88, vcc, s34, v86
	s_nop 1
	v_addc_co_u32_e32 v89, vcc, 0, v87, vcc
	v_add_co_u32_e32 v90, vcc, s35, v86
	s_nop 1
	v_addc_co_u32_e32 v91, vcc, 0, v87, vcc
	v_add_co_u32_e32 v144, vcc, s36, v86
	global_load_ushort v125, v[118:119], off offset:-4096
	global_load_ushort v121, v[118:119], off
	global_load_ushort v122, v[118:119], off offset:1024
	global_load_ushort v123, v[118:119], off offset:2048
	global_load_ushort v124, v[118:119], off offset:3072
	s_nop 0
	global_load_ushort v118, v[90:91], off offset:-4096
	global_load_ushort v119, v[90:91], off
	global_load_ushort v120, v[90:91], off offset:1024
	v_addc_co_u32_e32 v145, vcc, 0, v87, vcc
	v_add_co_u32_e32 v134, vcc, s37, v86
	s_nop 1
	v_addc_co_u32_e32 v135, vcc, 0, v87, vcc
	v_add_co_u32_e32 v150, vcc, s38, v86
	s_nop 1
	v_addc_co_u32_e32 v151, vcc, 0, v87, vcc
	v_add_co_u32_e32 v146, vcc, s39, v86
	s_nop 1
	v_addc_co_u32_e32 v147, vcc, 0, v87, vcc
	global_load_ushort v131, v[90:91], off offset:2048
	global_load_ushort v133, v[90:91], off offset:3072
	global_load_ushort v132, v[134:135], off offset:-4096
	global_load_ushort v126, v[134:135], off
	global_load_ushort v128, v[134:135], off offset:1024
	global_load_ushort v127, v[134:135], off offset:2048
; __device__ __forceinline__ void hg_a2_quad(unsigned char* ws, float* Gp, LAS unsigned char* lds, int quad, int tid) {
;     ...
;         for (int i = 0; i < 64; ++i) lf[i] = (float)lfp[(size_t)i * 512];
; #pragma unroll
;         for (int i = 0; i < 32; ++i) vq[i] = (unsigned)vp[(size_t)(2 * i) * 512] | ((unsigned)vp[(size_t)(2 * i + 1) * 512] << 16);
;         if (gi > 0) { float* pp = Gp + (size_t)unit * 16384 + (size_t)(wave * 8) * 256 + lane * 4;
; #pragma unroll
;             for (int kt = 0; kt < 8; ++kt) *(f32x4*)(pp + kt * 256) = R[kt]; }
	global_load_ushort v129, v[134:135], off offset:3072
	global_load_ushort v130, v[146:147], off offset:-4096
	global_load_ushort v148, v[86:87], off offset:3072
	global_load_ushort v141, v[88:89], off offset:1024
	global_load_ushort v138, v[88:89], off offset:2048
	global_load_ushort v142, v[88:89], off offset:3072
	global_load_ushort v136, v[144:145], off offset:1024
	global_load_ushort v135, v[144:145], off offset:2048
	global_load_ushort v137, v[144:145], off offset:3072
	global_load_ushort v134, v[150:151], off offset:1024
	v_add_co_u32_e32 v88, vcc, s40, v86
	s_nop 1
	v_addc_co_u32_e32 v89, vcc, 0, v87, vcc
	v_add_co_u32_e32 v90, vcc, s41, v86
	s_nop 1
	v_addc_co_u32_e32 v91, vcc, 0, v87, vcc
	v_add_co_u32_e32 v158, vcc, s42, v86
	global_load_ushort v139, v[146:147], off
	global_load_ushort v143, v[146:147], off offset:1024
	global_load_ushort v140, v[146:147], off offset:2048
	global_load_ushort v144, v[146:147], off offset:3072
	global_load_ushort v145, v[90:91], off offset:-4096
	s_nop 0
	global_load_ushort v146, v[90:91], off
	global_load_ushort v149, v[90:91], off offset:1024
	global_load_ushort v147, v[90:91], off offset:2048
	v_addc_co_u32_e32 v159, vcc, 0, v87, vcc
	v_add_co_u32_e32 v162, vcc, s43, v86
	global_load_ushort v156, v[150:151], off offset:2048
	global_load_ushort v157, v[150:151], off offset:3072
	global_load_ushort v154, v[88:89], off offset:1024
	s_nop 0
	global_load_ushort v151, v[88:89], off offset:2048
	global_load_ushort v155, v[88:89], off offset:3072
	global_load_ushort v152, v[158:159], off offset:1024
	global_load_ushort v150, v[158:159], off offset:2048
	global_load_ushort v153, v[158:159], off offset:3072
	v_addc_co_u32_e32 v163, vcc, 0, v87, vcc
	v_add_co_u32_e32 v88, vcc, s61, v86
	s_nop 1
	v_addc_co_u32_e32 v89, vcc, 0, v87, vcc
	v_add_co_u32_e32 v168, vcc, s62, v86
	s_nop 1
	v_addc_co_u32_e32 v169, vcc, 0, v87, vcc
	global_load_ushort v165, v[90:91], off offset:3072
	global_load_ushort v164, v[162:163], off offset:-4096
	global_load_ushort v158, v[162:163], off
	global_load_ushort v160, v[162:163], off offset:1024
	global_load_ushort v159, v[162:163], off offset:2048
	global_load_ushort v161, v[162:163], off offset:3072
	s_nop 0
	global_load_ushort v162, v[168:169], off offset:-4096
	global_load_ushort v163, v[168:169], off
	v_add_co_u32_e32 v90, vcc, s63, v86
	s_nop 1
	v_addc_co_u32_e32 v91, vcc, 0, v87, vcc
	v_add_co_u32_e32 v174, vcc, s64, v86
	s_nop 1
	v_addc_co_u32_e32 v175, vcc, 0, v87, vcc
	v_add_co_u32_e32 v182, vcc, 0xf000, v86
	global_load_ushort v167, v[168:169], off offset:1024
	global_load_ushort v166, v[168:169], off offset:2048
	s_nop 0
	global_load_ushort v168, v[168:169], off offset:3072
	s_nop 0
	global_load_ushort v169, v[174:175], off offset:-4096
	global_load_ushort v170, v[174:175], off
	global_load_ushort v172, v[174:175], off offset:1024
	global_load_ushort v171, v[174:175], off offset:2048
	global_load_ushort v173, v[174:175], off offset:3072
	v_addc_co_u32_e32 v183, vcc, 0, v87, vcc
	global_load_ushort v180, v[88:89], off offset:1024
	global_load_ushort v179, v[88:89], off offset:2048
	global_load_ushort v181, v[88:89], off offset:3072
	global_load_ushort v177, v[90:91], off offset:1024
	global_load_ushort v175, v[90:91], off offset:2048
	global_load_ushort v178, v[90:91], off offset:3072
	global_load_ushort v174, v[182:183], off
	global_load_ushort v176, v[182:183], off offset:1024
	s_nop 0
	global_load_ushort v90, v[38:39], off offset:-4096
	global_load_ushort v85, v[38:39], off
	global_load_ushort v86, v[38:39], off offset:1024
	global_load_ushort v87, v[38:39], off offset:2048
	global_load_ushort v88, v[38:39], off offset:3072
	global_load_ushort v89, v[40:41], off offset:-4096
	s_nop 0
	global_load_ushort v38, v[182:183], off offset:2048
	global_load_ushort v40, v[182:183], off offset:3072
	s_cbranch_scc1 .LBB0_581
	s_add_i32 s22, s28, s66
	s_ashr_i32 s23, s22, 31
	s_lshl_b64 s[22:23], s[22:23], 16
	v_lshl_add_u64 v[182:183], v[34:35], 0, s[22:23]
	global_store_dwordx4 v[182:183], v[28:31], off sc1
	global_store_dwordx4 v[182:183], v[24:27], off offset:1024 sc1
	global_store_dwordx4 v[182:183], v[16:19], off offset:2048 sc1
	global_store_dwordx4 v[182:183], v[20:23], off offset:3072 sc1
	v_add_co_u32_e32 v182, vcc, 0x1000, v182
	s_nop 1
	v_addc_co_u32_e32 v183, vcc, 0, v183, vcc
	global_store_dwordx4 v[182:183], v[8:11], off sc1
	global_store_dwordx4 v[182:183], v[4:7], off offset:1024 sc1
	global_store_dwordx4 v[182:183], v[0:3], off offset:2048 sc1
	global_store_dwordx4 v[182:183], v[12:15], off offset:3072 sc1
; __device__ __forceinline__ void hg_a2_quad(unsigned char* ws, float* Gp, LAS unsigned char* lds, int quad, int tid) {
;     ...
;         for (int i = 0; i < 64; ++i) lf[i] = (float)lfp[(size_t)i * 512];
; #pragma unroll
;         for (int i = 0; i < 32; ++i) vq[i] = (unsigned)vp[(size_t)(2 * i) * 512] | ((unsigned)vp[(size_t)(2 * i + 1) * 512] << 16);
;         if (gi > 0) { float* pp = Gp + (size_t)unit * 16384 + (size_t)(wave * 8) * 256 + lane * 4;
; #pragma unroll
;             for (int kt = 0; kt < 8; ++kt) *(f32x4*)(pp + kt * 256) = R[kt]; }
;         float run = 0.f;
; #pragma unroll
;         for (int i = 0; i < 64; ++i) run += lf[i];
.LBB0_581:
	s_waitcnt vmcnt(62)
	v_cvt_f32_f16_e32 v182, v59
	v_cvt_f32_f16_e32 v183, v60
	v_cvt_f32_f16_e32 v184, v61
	v_cvt_f32_f16_e32 v185, v62
	s_waitcnt vmcnt(0)
	v_lshlrev_b32_e32 v40, 16, v40
	v_cvt_f32_f16_e32 v186, v90
	v_cvt_f32_f16_e32 v60, v123
	v_or_b32_sdwa v123, v40, v38 dst_sel:DWORD dst_unused:UNUSED_PAD src0_sel:DWORD src1_sel:WORD_0
	v_add_f32_e32 v38, 0, v182
	v_cvt_f32_f16_e32 v187, v56
	v_add_f32_e32 v38, v38, v183
	v_cvt_f32_f16_e32 v39, v57
	v_add_f32_e32 v38, v38, v184
	v_cvt_f32_f16_e32 v41, v58
	v_add_f32_e32 v38, v38, v185
	v_cvt_f32_f16_e32 v188, v85
	v_add_f32_e32 v38, v38, v186
	v_cvt_f32_f16_e32 v189, v86
	v_add_f32_e32 v38, v38, v187
	v_cvt_f32_f16_e32 v190, v87
	v_add_f32_e32 v38, v38, v39
	v_cvt_f32_f16_e32 v191, v88
	v_add_f32_e32 v38, v38, v41
	v_cvt_f32_f16_e32 v192, v89
	v_add_f32_e32 v38, v38, v188
	v_cvt_f32_f16_e32 v193, v37
	v_add_f32_e32 v38, v38, v189
	v_cvt_f32_f16_e32 v194, v77
	v_add_f32_e32 v38, v38, v190
	v_cvt_f32_f16_e32 v195, v78
	v_add_f32_e32 v38, v38, v191
	v_cvt_f32_f16_e32 v196, v63
	v_add_f32_e32 v38, v38, v192
	v_cvt_f32_f16_e32 v197, v64
	v_add_f32_e32 v38, v38, v193
	v_cvt_f32_f16_e32 v198, v65
	v_add_f32_e32 v38, v38, v194
	v_cvt_f32_f16_e32 v199, v66
	v_add_f32_e32 v38, v38, v195
	v_cvt_f32_f16_e32 v200, v67
	v_add_f32_e32 v38, v38, v196
	v_cvt_f32_f16_e32 v201, v74
	v_add_f32_e32 v38, v38, v197
	v_cvt_f32_f16_e32 v202, v75
	v_add_f32_e32 v38, v38, v198
	v_cvt_f32_f16_e32 v203, v76
	v_add_f32_e32 v38, v38, v199
	v_cvt_f32_f16_e32 v204, v68
	v_add_f32_e32 v38, v38, v200
	v_cvt_f32_f16_e32 v205, v69
	v_add_f32_e32 v38, v38, v201
	v_cvt_f32_f16_e32 v206, v70
	v_add_f32_e32 v38, v38, v202
	v_cvt_f32_f16_e32 v91, v83
	v_add_f32_e32 v38, v38, v203
	v_cvt_f32_f16_e32 v90, v84
	v_add_f32_e32 v38, v38, v204
	v_cvt_f32_f16_e32 v89, v71
	v_add_f32_e32 v38, v38, v205
	v_cvt_f32_f16_e32 v88, v72
	v_add_f32_e32 v38, v38, v206
	v_cvt_f32_f16_e32 v87, v73
	v_add_f32_e32 v38, v38, v91
	v_cvt_f32_f16_e32 v86, v79
	v_add_f32_e32 v38, v38, v90
	v_cvt_f32_f16_e32 v85, v80
	v_add_f32_e32 v38, v38, v89
	v_cvt_f32_f16_e32 v84, v81
	v_add_f32_e32 v38, v38, v88
	v_cvt_f32_f16_e32 v83, v82
	v_add_f32_e32 v38, v38, v87
	v_cvt_f32_f16_e32 v82, v92
	v_add_f32_e32 v38, v38, v86
	v_cvt_f32_f16_e32 v81, v107
	v_add_f32_e32 v38, v38, v85
	v_cvt_f32_f16_e32 v80, v108
	v_add_f32_e32 v38, v38, v84
	v_cvt_f32_f16_e32 v79, v109
	v_add_f32_e32 v38, v38, v83
	v_cvt_f32_f16_e32 v78, v93
	v_add_f32_e32 v38, v38, v82
	v_cvt_f32_f16_e32 v77, v94
	v_add_f32_e32 v38, v38, v81
	v_cvt_f32_f16_e32 v76, v95
	v_add_f32_e32 v38, v38, v80
	v_cvt_f32_f16_e32 v75, v96
	v_add_f32_e32 v38, v38, v79
	v_cvt_f32_f16_e32 v74, v97
	v_add_f32_e32 v38, v38, v78
	v_cvt_f32_f16_e32 v73, v104
	v_add_f32_e32 v38, v38, v77
	v_cvt_f32_f16_e32 v72, v105
	v_add_f32_e32 v38, v38, v76
	v_cvt_f32_f16_e32 v71, v106
	v_add_f32_e32 v38, v38, v75
	v_cvt_f32_f16_e32 v70, v98
	v_add_f32_e32 v38, v38, v74
	v_cvt_f32_f16_e32 v69, v99
	v_add_f32_e32 v38, v38, v73
	v_cvt_f32_f16_e32 v68, v100
	v_add_f32_e32 v38, v38, v72
	v_cvt_f32_f16_e32 v67, v101
	v_add_f32_e32 v38, v38, v71
	v_cvt_f32_f16_e32 v66, v125
	v_add_f32_e32 v38, v38, v70
	v_cvt_f32_f16_e32 v65, v102
	v_add_f32_e32 v38, v38, v69
	v_cvt_f32_f16_e32 v64, v103
	v_add_f32_e32 v38, v38, v68
	v_cvt_f32_f16_e32 v63, v117
	v_add_f32_e32 v38, v38, v67
	v_cvt_f32_f16_e32 v62, v121
	v_add_f32_e32 v38, v38, v66
	v_cvt_f32_f16_e32 v61, v122
	v_add_f32_e32 v38, v38, v65
	v_add_f32_e32 v38, v38, v64
	v_cvt_f32_f16_e32 v59, v124
	v_add_f32_e32 v38, v38, v63
	v_cvt_f32_f16_e32 v58, v112
	v_add_f32_e32 v38, v38, v62
	v_cvt_f32_f16_e32 v57, v113
	v_add_f32_e32 v38, v38, v61
	v_cvt_f32_f16_e32 v56, v114
	v_add_f32_e32 v38, v38, v60
	v_cvt_f32_f16_e32 v37, v115
	v_add_f32_e32 v38, v38, v59
	v_add_f32_e32 v38, v38, v58
	v_add_f32_e32 v38, v38, v57
	v_lshlrev_b32_e32 v92, 16, v116
	v_lshlrev_b32_e32 v93, 16, v148
	v_lshlrev_b32_e32 v94, 16, v141
	v_lshlrev_b32_e32 v96, 16, v120
	v_add_f32_e32 v38, v38, v56
	v_or_b32_sdwa v92, v92, v110 dst_sel:DWORD dst_unused:UNUSED_PAD src0_sel:DWORD src1_sel:WORD_0
	v_or_b32_sdwa v93, v93, v111 dst_sel:DWORD dst_unused:UNUSED_PAD src0_sel:DWORD src1_sel:WORD_0
	v_or_b32_sdwa v94, v94, v118 dst_sel:DWORD dst_unused:UNUSED_PAD src0_sel:DWORD src1_sel:WORD_0
	v_lshlrev_b32_e32 v95, 16, v142
	v_or_b32_sdwa v96, v96, v119 dst_sel:DWORD dst_unused:UNUSED_PAD src0_sel:DWORD src1_sel:WORD_0
	v_lshlrev_b32_e32 v97, 16, v133
	v_lshlrev_b32_e32 v98, 16, v136
	v_lshlrev_b32_e32 v99, 16, v137
	v_lshlrev_b32_e32 v100, 16, v128
	v_lshlrev_b32_e32 v101, 16, v129
	v_lshlrev_b32_e32 v102, 16, v134
	v_lshlrev_b32_e32 v103, 16, v157
	v_lshlrev_b32_e32 v104, 16, v143
	v_lshlrev_b32_e32 v105, 16, v144
	v_lshlrev_b32_e32 v106, 16, v154
	v_lshlrev_b32_e32 v107, 16, v155
	v_lshlrev_b32_e32 v108, 16, v149
	v_lshlrev_b32_e32 v109, 16, v165
	v_lshlrev_b32_e32 v110, 16, v152
	v_lshlrev_b32_e32 v111, 16, v153
	v_lshlrev_b32_e32 v112, 16, v160
	v_lshlrev_b32_e32 v113, 16, v161
	v_lshlrev_b32_e32 v114, 16, v180
	v_lshlrev_b32_e32 v115, 16, v181
	v_lshlrev_b32_e32 v116, 16, v167
	v_lshlrev_b32_e32 v117, 16, v168
	v_lshlrev_b32_e32 v118, 16, v177
	v_lshlrev_b32_e32 v119, 16, v178
	v_lshlrev_b32_e32 v120, 16, v172
	v_lshlrev_b32_e32 v121, 16, v173
	v_lshlrev_b32_e32 v122, 16, v176
	v_add_f32_e32 v38, v38, v37
	v_or_b32_sdwa v95, v95, v138 dst_sel:DWORD dst_unused:UNUSED_PAD src0_sel:DWORD src1_sel:WORD_0
	v_or_b32_sdwa v97, v97, v131 dst_sel:DWORD dst_unused:UNUSED_PAD src0_sel:DWORD src1_sel:WORD_0
	v_or_b32_sdwa v98, v98, v132 dst_sel:DWORD dst_unused:UNUSED_PAD src0_sel:DWORD src1_sel:WORD_0
; #define LAS __attribute__((address_space(3)))
; __device__ __forceinline__ unsigned pk2(float lo, float hi) { return pg8::cvt_pk_bf16(lo, hi); }
; #define LBAR() do { asm volatile("s_waitcnt lgkmcnt(0)" ::: "memory"); __builtin_amdgcn_s_barrier(); asm volatile("" ::: "memory"); } while (0)
; __device__ __forceinline__ void hg_a2_quad(unsigned char* ws, float* Gp, LAS unsigned char* lds, int quad, int tid) {
;     ...
;         for (int i = 0; i < 64; ++i) run += lf[i];
;         segsum[seg * 128 + k] = run;
; #pragma unroll
;         for (int i = 0; i < 8; ++i) *(LAS v4u*)(Vt + k * GP + seg * 64 + 8 * i) = (v4u){vq[4 * i], vq[4 * i + 1], vq[4 * i + 2], vq[4 * i + 3]};
;         LBAR();
;         const float s0 = segsum[k], s1 = segsum[128 + k], s2 = segsum[256 + k], s3 = segsum[384 + k];
;         const float pre = (seg > 0 ? s0 : 0.f) + (seg > 1 ? s1 : 0.f) + (seg > 2 ? s2 : 0.f);
;         const float blast = (s0 + s1) + (s2 + s3);
;         run = pre;
; #pragma unroll
;         for (int i8 = 0; i8 < 8; ++i8) { unsigned kp[4];
; #pragma unroll
;             for (int j = 0; j < 4; ++j) { const float l0 = lf[8 * i8 + 2 * j], l1 = lf[8 * i8 + 2 * j + 1]; run += l0; const float a0 = (1.f - __expf(l0)) * __expf(blast - run); run += l1; const float a1 = (1.f - __expf(l1)) * __expf(blast - run); kp[j] = pk2(a0, a1); }
;             *(LAS v4u*)(KPt + k * GP + seg * 64 + 8 * i8) = (v4u){kp[0], kp[1], kp[2], kp[3]}; }
	v_or_b32_sdwa v99, v99, v135 dst_sel:DWORD dst_unused:UNUSED_PAD src0_sel:DWORD src1_sel:WORD_0
	v_or_b32_sdwa v100, v100, v126 dst_sel:DWORD dst_unused:UNUSED_PAD src0_sel:DWORD src1_sel:WORD_0
	v_or_b32_sdwa v101, v101, v127 dst_sel:DWORD dst_unused:UNUSED_PAD src0_sel:DWORD src1_sel:WORD_0
	v_or_b32_sdwa v102, v102, v130 dst_sel:DWORD dst_unused:UNUSED_PAD src0_sel:DWORD src1_sel:WORD_0
	v_or_b32_sdwa v103, v103, v156 dst_sel:DWORD dst_unused:UNUSED_PAD src0_sel:DWORD src1_sel:WORD_0
	v_or_b32_sdwa v104, v104, v139 dst_sel:DWORD dst_unused:UNUSED_PAD src0_sel:DWORD src1_sel:WORD_0
	v_or_b32_sdwa v105, v105, v140 dst_sel:DWORD dst_unused:UNUSED_PAD src0_sel:DWORD src1_sel:WORD_0
	v_or_b32_sdwa v106, v106, v145 dst_sel:DWORD dst_unused:UNUSED_PAD src0_sel:DWORD src1_sel:WORD_0
	v_or_b32_sdwa v107, v107, v151 dst_sel:DWORD dst_unused:UNUSED_PAD src0_sel:DWORD src1_sel:WORD_0
	v_or_b32_sdwa v108, v108, v146 dst_sel:DWORD dst_unused:UNUSED_PAD src0_sel:DWORD src1_sel:WORD_0
	v_or_b32_sdwa v109, v109, v147 dst_sel:DWORD dst_unused:UNUSED_PAD src0_sel:DWORD src1_sel:WORD_0
	v_or_b32_sdwa v110, v110, v164 dst_sel:DWORD dst_unused:UNUSED_PAD src0_sel:DWORD src1_sel:WORD_0
	v_or_b32_sdwa v111, v111, v150 dst_sel:DWORD dst_unused:UNUSED_PAD src0_sel:DWORD src1_sel:WORD_0
	v_or_b32_sdwa v112, v112, v158 dst_sel:DWORD dst_unused:UNUSED_PAD src0_sel:DWORD src1_sel:WORD_0
	v_or_b32_sdwa v113, v113, v159 dst_sel:DWORD dst_unused:UNUSED_PAD src0_sel:DWORD src1_sel:WORD_0
	v_or_b32_sdwa v114, v114, v162 dst_sel:DWORD dst_unused:UNUSED_PAD src0_sel:DWORD src1_sel:WORD_0
	v_or_b32_sdwa v115, v115, v179 dst_sel:DWORD dst_unused:UNUSED_PAD src0_sel:DWORD src1_sel:WORD_0
	v_or_b32_sdwa v116, v116, v163 dst_sel:DWORD dst_unused:UNUSED_PAD src0_sel:DWORD src1_sel:WORD_0
	v_or_b32_sdwa v117, v117, v166 dst_sel:DWORD dst_unused:UNUSED_PAD src0_sel:DWORD src1_sel:WORD_0
	v_or_b32_sdwa v118, v118, v169 dst_sel:DWORD dst_unused:UNUSED_PAD src0_sel:DWORD src1_sel:WORD_0
	v_or_b32_sdwa v119, v119, v175 dst_sel:DWORD dst_unused:UNUSED_PAD src0_sel:DWORD src1_sel:WORD_0
	v_or_b32_sdwa v120, v120, v170 dst_sel:DWORD dst_unused:UNUSED_PAD src0_sel:DWORD src1_sel:WORD_0
	v_or_b32_sdwa v121, v121, v171 dst_sel:DWORD dst_unused:UNUSED_PAD src0_sel:DWORD src1_sel:WORD_0
	v_or_b32_sdwa v122, v122, v174 dst_sel:DWORD dst_unused:UNUSED_PAD src0_sel:DWORD src1_sel:WORD_0
	ds_write_b32 v47, v38
	ds_write_b128 v48, v[92:95]
	ds_write_b128 v48, v[96:99] offset:16
	ds_write_b128 v48, v[100:103] offset:32
	ds_write_b128 v48, v[104:107] offset:48
	ds_write_b128 v48, v[108:111] offset:64
	ds_write_b128 v48, v[112:115] offset:80
	ds_write_b128 v48, v[116:119] offset:96
	ds_write_b128 v48, v[120:123] offset:112
	s_waitcnt lgkmcnt(0)
	s_barrier
	ds_read2st64_b32 v[92:93], v49 offset1:2
	ds_read2st64_b32 v[94:95], v49 offset0:4 offset1:6
	v_mul_f32_e32 v109, 0x3fb8aa3b, v39
	s_waitcnt lgkmcnt(1)
	v_cndmask_b32_e64 v38, v92, 0, s[4:5]
	v_cndmask_b32_e64 v40, 0, v93, s[6:7]
	v_add_f32_e32 v38, v38, v40
	s_waitcnt lgkmcnt(0)
	v_cndmask_b32_e64 v40, 0, v94, s[8:9]
	v_add_f32_e32 v38, v38, v40
	v_mul_f32_e32 v40, 0x3fb8aa3b, v182
	v_exp_f32_e32 v96, v40
	v_mul_f32_e32 v40, 0x3fb8aa3b, v183
	v_exp_f32_e32 v97, v40
	v_add_f32_e32 v104, v38, v182
	v_add_f32_e32 v105, v104, v183
	v_mul_f32_e32 v38, 0x3fb8aa3b, v184
	v_add_f32_e32 v40, v94, v95
	v_pk_add_f32 v[94:95], v[96:97], 1.0 op_sel_hi:[1,0] neg_lo:[1,0] neg_hi:[1,0]
	v_add_f32_e32 v106, v105, v184
	v_exp_f32_e32 v96, v38
	v_mul_f32_e32 v38, 0x3fb8aa3b, v185
	v_add_f32_e32 v107, v106, v185
	v_exp_f32_e32 v97, v38
	v_mul_f32_e32 v38, 0x3fb8aa3b, v186
	v_exp_f32_e32 v98, v38
	v_mul_f32_e32 v38, 0x3fb8aa3b, v187
	v_add_f32_e32 v108, v107, v186
	v_exp_f32_e32 v99, v38
	v_add_f32_e32 v101, v108, v187
	v_mov_b32_e32 v100, v92
	v_mov_b32_e32 v38, v93
	v_pk_add_f32 v[102:103], v[100:101], v[38:39]
	v_pk_add_f32 v[96:97], v[96:97], 1.0 op_sel_hi:[1,0] neg_lo:[1,0] neg_hi:[1,0]
	v_pk_add_f32 v[38:39], v[102:103], v[40:41]
	v_mul_f32_e32 v41, 0x3fb8aa3b, v41
	v_sub_f32_e32 v40, v38, v104
	v_mul_f32_e32 v40, 0x3fb8aa3b, v40
	v_exp_f32_e32 v92, v40
	v_sub_f32_e32 v40, v38, v105
	v_mul_f32_e32 v40, 0x3fb8aa3b, v40
	v_exp_f32_e32 v93, v40
	v_sub_f32_e32 v40, v38, v106
	v_mul_f32_e32 v40, 0x3fb8aa3b, v40
	v_exp_f32_e32 v104, v40
	v_sub_f32_e32 v40, v38, v107
	v_mul_f32_e32 v40, 0x3fb8aa3b, v40
	v_exp_f32_e32 v105, v40
	v_pk_mul_f32 v[92:93], v[94:95], v[92:93]
	v_exp_f32_e32 v40, v109
	v_cvt_pk_bf16_f32 v92, v92, v93
	v_pk_mul_f32 v[94:95], v[96:97], v[104:105]
	v_sub_f32_e32 v96, v38, v103
	v_cvt_pk_bf16_f32 v93, v94, v95
	v_sub_f32_e32 v94, v38, v108
	v_sub_f32_e32 v95, v38, v101
	v_sub_f32_e32 v97, v38, v39
	v_mul_f32_e32 v94, 0x3fb8aa3b, v94
	v_mul_f32_e32 v95, 0x3fb8aa3b, v95
	v_mul_f32_e32 v96, 0x3fb8aa3b, v96
	v_exp_f32_e32 v41, v41
	v_mul_f32_e32 v97, 0x3fb8aa3b, v97
	v_exp_f32_e32 v94, v94
	v_exp_f32_e32 v95, v95
	v_exp_f32_e32 v96, v96
	v_exp_f32_e32 v97, v97
	v_pk_add_f32 v[98:99], v[98:99], 1.0 op_sel_hi:[1,0] neg_lo:[1,0] neg_hi:[1,0]
	v_pk_add_f32 v[40:41], v[40:41], 1.0 op_sel_hi:[1,0] neg_lo:[1,0] neg_hi:[1,0]
	v_pk_mul_f32 v[94:95], v[98:99], v[94:95]
	v_pk_mul_f32 v[40:41], v[40:41], v[96:97]
	v_add_f32_e32 v39, v39, v188
	v_cvt_pk_bf16_f32 v94, v94, v95
	v_cvt_pk_bf16_f32 v95, v40, v41
	v_sub_f32_e32 v41, v38, v39
	v_add_f32_e32 v39, v39, v189
	ds_write_b128 v53, v[92:95] offset:2560
	v_mul_f32_e32 v41, 0x3fb8aa3b, v41
	v_sub_f32_e32 v93, v38, v39
	v_add_f32_e32 v39, v39, v190
	v_mul_f32_e32 v40, 0x3fb8aa3b, v188
	v_exp_f32_e32 v92, v41
	v_mul_f32_e32 v41, 0x3fb8aa3b, v189
	v_sub_f32_e32 v95, v38, v39
	v_exp_f32_e32 v40, v40
; #define LAS __attribute__((address_space(3)))
; __device__ __forceinline__ unsigned pk2(float lo, float hi) { return pg8::cvt_pk_bf16(lo, hi); }
; __device__ __forceinline__ void hg_a2_quad(unsigned char* ws, float* Gp, LAS unsigned char* lds, int quad, int tid) {
;     ...
; #pragma unroll
;         for (int i8 = 0; i8 < 8; ++i8) { unsigned kp[4];
; #pragma unroll
;             for (int j = 0; j < 4; ++j) { const float l0 = lf[8 * i8 + 2 * j], l1 = lf[8 * i8 + 2 * j + 1]; run += l0; const float a0 = (1.f - __expf(l0)) * __expf(blast - run); run += l1; const float a1 = (1.f - __expf(l1)) * __expf(blast - run); kp[j] = pk2(a0, a1); }
;             *(LAS v4u*)(KPt + k * GP + seg * 64 + 8 * i8) = (v4u){kp[0], kp[1], kp[2], kp[3]}; }
	v_exp_f32_e32 v41, v41
	v_mul_f32_e32 v93, 0x3fb8aa3b, v93
	v_mul_f32_e32 v95, 0x3fb8aa3b, v95
	v_add_f32_e32 v39, v39, v191
	v_exp_f32_e32 v93, v93
	v_mul_f32_e32 v94, 0x3fb8aa3b, v190
	v_exp_f32_e32 v96, v95
	v_mul_f32_e32 v95, 0x3fb8aa3b, v191
	v_sub_f32_e32 v97, v38, v39
	v_exp_f32_e32 v94, v94
	v_exp_f32_e32 v95, v95
	v_mul_f32_e32 v97, 0x3fb8aa3b, v97
	v_exp_f32_e32 v97, v97
	v_pk_add_f32 v[40:41], v[40:41], 1.0 op_sel_hi:[1,0] neg_lo:[1,0] neg_hi:[1,0]
	v_add_f32_e32 v39, v39, v192
	v_pk_mul_f32 v[40:41], v[40:41], v[92:93]
	s_nop 0
	v_cvt_pk_bf16_f32 v92, v40, v41
	v_pk_add_f32 v[40:41], v[94:95], 1.0 op_sel_hi:[1,0] neg_lo:[1,0] neg_hi:[1,0]
	s_nop 0
	v_pk_mul_f32 v[40:41], v[40:41], v[96:97]
	v_mul_f32_e32 v96, 0x3fb8aa3b, v194
	v_cvt_pk_bf16_f32 v93, v40, v41
	v_sub_f32_e32 v41, v38, v39
	v_add_f32_e32 v39, v39, v193
	v_mul_f32_e32 v41, 0x3fb8aa3b, v41
	v_sub_f32_e32 v95, v38, v39
	v_add_f32_e32 v39, v39, v194
	v_mul_f32_e32 v40, 0x3fb8aa3b, v192
	v_exp_f32_e32 v94, v41
	v_mul_f32_e32 v41, 0x3fb8aa3b, v193
	v_sub_f32_e32 v97, v38, v39
	v_exp_f32_e32 v40, v40
	v_exp_f32_e32 v41, v41
	v_mul_f32_e32 v95, 0x3fb8aa3b, v95
	v_mul_f32_e32 v97, 0x3fb8aa3b, v97
	v_add_f32_e32 v39, v39, v195
	v_exp_f32_e32 v95, v95
	v_exp_f32_e32 v98, v97
	v_mul_f32_e32 v97, 0x3fb8aa3b, v195
	v_sub_f32_e32 v99, v38, v39
	v_exp_f32_e32 v96, v96
	v_exp_f32_e32 v97, v97
	v_mul_f32_e32 v99, 0x3fb8aa3b, v99
	v_exp_f32_e32 v99, v99
	v_pk_add_f32 v[40:41], v[40:41], 1.0 op_sel_hi:[1,0] neg_lo:[1,0] neg_hi:[1,0]
	v_add_f32_e32 v39, v39, v196
	v_pk_mul_f32 v[40:41], v[40:41], v[94:95]
	s_nop 0
	v_cvt_pk_bf16_f32 v94, v40, v41
	v_pk_add_f32 v[40:41], v[96:97], 1.0 op_sel_hi:[1,0] neg_lo:[1,0] neg_hi:[1,0]
	s_nop 0
	v_pk_mul_f32 v[40:41], v[40:41], v[98:99]
	s_nop 0
	v_cvt_pk_bf16_f32 v95, v40, v41
	v_sub_f32_e32 v41, v38, v39
	v_add_f32_e32 v39, v39, v197
	ds_write_b128 v53, v[92:95] offset:2576
	v_mul_f32_e32 v41, 0x3fb8aa3b, v41
	v_sub_f32_e32 v93, v38, v39
	v_add_f32_e32 v39, v39, v198
	v_mul_f32_e32 v40, 0x3fb8aa3b, v196
	v_exp_f32_e32 v92, v41
	v_mul_f32_e32 v41, 0x3fb8aa3b, v197
	v_sub_f32_e32 v95, v38, v39
	v_exp_f32_e32 v40, v40
	v_exp_f32_e32 v41, v41
	v_mul_f32_e32 v93, 0x3fb8aa3b, v93
	v_mul_f32_e32 v95, 0x3fb8aa3b, v95
	v_add_f32_e32 v39, v39, v199
	v_exp_f32_e32 v93, v93
	v_mul_f32_e32 v94, 0x3fb8aa3b, v198
	v_exp_f32_e32 v96, v95
	v_mul_f32_e32 v95, 0x3fb8aa3b, v199
	v_sub_f32_e32 v97, v38, v39
	v_exp_f32_e32 v94, v94
	v_exp_f32_e32 v95, v95
	v_mul_f32_e32 v97, 0x3fb8aa3b, v97
	v_exp_f32_e32 v97, v97
	v_pk_add_f32 v[40:41], v[40:41], 1.0 op_sel_hi:[1,0] neg_lo:[1,0] neg_hi:[1,0]
	v_add_f32_e32 v39, v39, v200
	v_pk_mul_f32 v[40:41], v[40:41], v[92:93]
	s_nop 0
	v_cvt_pk_bf16_f32 v92, v40, v41
	v_pk_add_f32 v[40:41], v[94:95], 1.0 op_sel_hi:[1,0] neg_lo:[1,0] neg_hi:[1,0]
	s_nop 0
	v_pk_mul_f32 v[40:41], v[40:41], v[96:97]
	v_mul_f32_e32 v96, 0x3fb8aa3b, v202
	v_cvt_pk_bf16_f32 v93, v40, v41
	v_sub_f32_e32 v41, v38, v39
	v_add_f32_e32 v39, v39, v201
	v_mul_f32_e32 v41, 0x3fb8aa3b, v41
	v_sub_f32_e32 v95, v38, v39
	v_add_f32_e32 v39, v39, v202
	v_mul_f32_e32 v40, 0x3fb8aa3b, v200
	v_exp_f32_e32 v94, v41
	v_mul_f32_e32 v41, 0x3fb8aa3b, v201
	v_sub_f32_e32 v97, v38, v39
	v_exp_f32_e32 v40, v40
	v_exp_f32_e32 v41, v41
	v_mul_f32_e32 v95, 0x3fb8aa3b, v95
	v_mul_f32_e32 v97, 0x3fb8aa3b, v97
	v_add_f32_e32 v39, v39, v203
	v_exp_f32_e32 v95, v95
	v_exp_f32_e32 v98, v97
	v_mul_f32_e32 v97, 0x3fb8aa3b, v203
	v_sub_f32_e32 v99, v38, v39
	v_exp_f32_e32 v96, v96
	v_exp_f32_e32 v97, v97
	v_mul_f32_e32 v99, 0x3fb8aa3b, v99
	v_exp_f32_e32 v99, v99
	v_pk_add_f32 v[40:41], v[40:41], 1.0 op_sel_hi:[1,0] neg_lo:[1,0] neg_hi:[1,0]
	v_add_f32_e32 v39, v39, v204
	v_pk_mul_f32 v[40:41], v[40:41], v[94:95]
	s_nop 0
	v_cvt_pk_bf16_f32 v94, v40, v41
	v_pk_add_f32 v[40:41], v[96:97], 1.0 op_sel_hi:[1,0] neg_lo:[1,0] neg_hi:[1,0]
	s_nop 0
	v_pk_mul_f32 v[40:41], v[40:41], v[98:99]
	s_nop 0
	v_cvt_pk_bf16_f32 v95, v40, v41
	v_sub_f32_e32 v41, v38, v39
	v_add_f32_e32 v39, v39, v205
	ds_write_b128 v53, v[92:95] offset:2592
	v_mul_f32_e32 v41, 0x3fb8aa3b, v41
	v_sub_f32_e32 v93, v38, v39
	v_add_f32_e32 v39, v39, v206
	v_mul_f32_e32 v40, 0x3fb8aa3b, v204
	v_exp_f32_e32 v92, v41
	v_mul_f32_e32 v41, 0x3fb8aa3b, v205
	v_sub_f32_e32 v95, v38, v39
	v_exp_f32_e32 v40, v40
	v_exp_f32_e32 v41, v41
	v_mul_f32_e32 v93, 0x3fb8aa3b, v93
	v_mul_f32_e32 v95, 0x3fb8aa3b, v95
	v_add_f32_e32 v39, v39, v91
	v_mul_f32_e32 v91, 0x3fb8aa3b, v91
	v_exp_f32_e32 v93, v93
	v_mul_f32_e32 v94, 0x3fb8aa3b, v206
	v_exp_f32_e32 v96, v95
	v_exp_f32_e32 v95, v91
	v_sub_f32_e32 v91, v38, v39
	v_exp_f32_e32 v94, v94
	v_mul_f32_e32 v91, 0x3fb8aa3b, v91
	v_exp_f32_e32 v97, v91
	v_pk_add_f32 v[40:41], v[40:41], 1.0 op_sel_hi:[1,0] neg_lo:[1,0] neg_hi:[1,0]
	v_add_f32_e32 v39, v39, v90
	v_pk_mul_f32 v[40:41], v[40:41], v[92:93]
	s_nop 0
	v_cvt_pk_bf16_f32 v92, v40, v41
	v_pk_add_f32 v[40:41], v[94:95], 1.0 op_sel_hi:[1,0] neg_lo:[1,0] neg_hi:[1,0]
	s_nop 0
	v_pk_mul_f32 v[40:41], v[40:41], v[96:97]
	s_nop 0
	v_cvt_pk_bf16_f32 v93, v40, v41
	v_sub_f32_e32 v41, v38, v39
	v_mul_f32_e32 v41, 0x3fb8aa3b, v41
	v_add_f32_e32 v39, v39, v89
	v_mul_f32_e32 v40, 0x3fb8aa3b, v90
	v_exp_f32_e32 v90, v41
	v_mul_f32_e32 v41, 0x3fb8aa3b, v89
	v_sub_f32_e32 v89, v38, v39
	v_mul_f32_e32 v89, 0x3fb8aa3b, v89
	v_add_f32_e32 v39, v39, v88
	v_exp_f32_e32 v91, v89
	v_sub_f32_e32 v89, v38, v39
	v_exp_f32_e32 v40, v40
	v_exp_f32_e32 v41, v41
	v_mul_f32_e32 v89, 0x3fb8aa3b, v89
	v_add_f32_e32 v39, v39, v87
	v_mul_f32_e32 v87, 0x3fb8aa3b, v87
	v_mul_f32_e32 v88, 0x3fb8aa3b, v88
	v_exp_f32_e32 v96, v89
	v_exp_f32_e32 v89, v87
	v_sub_f32_e32 v87, v38, v39
; #define LAS __attribute__((address_space(3)))
; __device__ __forceinline__ unsigned pk2(float lo, float hi) { return pg8::cvt_pk_bf16(lo, hi); }
; __device__ __forceinline__ void hg_a2_quad(unsigned char* ws, float* Gp, LAS unsigned char* lds, int quad, int tid) {
;     ...
; #pragma unroll
;         for (int i8 = 0; i8 < 8; ++i8) { unsigned kp[4];
; #pragma unroll
;             for (int j = 0; j < 4; ++j) { const float l0 = lf[8 * i8 + 2 * j], l1 = lf[8 * i8 + 2 * j + 1]; run += l0; const float a0 = (1.f - __expf(l0)) * __expf(blast - run); run += l1; const float a1 = (1.f - __expf(l1)) * __expf(blast - run); kp[j] = pk2(a0, a1); }
;             *(LAS v4u*)(KPt + k * GP + seg * 64 + 8 * i8) = (v4u){kp[0], kp[1], kp[2], kp[3]}; }
	v_exp_f32_e32 v88, v88
	v_mul_f32_e32 v87, 0x3fb8aa3b, v87
	v_exp_f32_e32 v97, v87
	v_pk_add_f32 v[40:41], v[40:41], 1.0 op_sel_hi:[1,0] neg_lo:[1,0] neg_hi:[1,0]
	v_add_f32_e32 v39, v39, v86
	v_pk_mul_f32 v[40:41], v[40:41], v[90:91]
	s_nop 0
	v_cvt_pk_bf16_f32 v94, v40, v41
	v_pk_add_f32 v[40:41], v[88:89], 1.0 op_sel_hi:[1,0] neg_lo:[1,0] neg_hi:[1,0]
	s_nop 0
	v_pk_mul_f32 v[40:41], v[40:41], v[96:97]
	s_nop 0
	v_cvt_pk_bf16_f32 v95, v40, v41
	v_sub_f32_e32 v41, v38, v39
	v_mul_f32_e32 v41, 0x3fb8aa3b, v41
	v_add_f32_e32 v39, v39, v85
	v_mul_f32_e32 v40, 0x3fb8aa3b, v86
	v_exp_f32_e32 v86, v41
	v_mul_f32_e32 v41, 0x3fb8aa3b, v85
	v_sub_f32_e32 v85, v38, v39
	v_add_f32_e32 v39, v39, v84
	v_mul_f32_e32 v84, 0x3fb8aa3b, v84
	v_exp_f32_e32 v40, v40
	v_exp_f32_e32 v41, v41
	v_mul_f32_e32 v85, 0x3fb8aa3b, v85
	v_exp_f32_e32 v88, v84
	v_sub_f32_e32 v84, v38, v39
	v_add_f32_e32 v39, v39, v83
	v_mul_f32_e32 v83, 0x3fb8aa3b, v83
	v_exp_f32_e32 v87, v85
	v_exp_f32_e32 v89, v83
	v_sub_f32_e32 v83, v38, v39
	v_mul_f32_e32 v84, 0x3fb8aa3b, v84
	v_mul_f32_e32 v83, 0x3fb8aa3b, v83
	v_exp_f32_e32 v90, v84
	v_exp_f32_e32 v91, v83
	v_pk_add_f32 v[40:41], v[40:41], 1.0 op_sel_hi:[1,0] neg_lo:[1,0] neg_hi:[1,0]
	v_add_f32_e32 v39, v39, v82
	v_pk_mul_f32 v[40:41], v[40:41], v[86:87]
	ds_write_b128 v53, v[92:95] offset:2608
	v_cvt_pk_bf16_f32 v84, v40, v41
	v_pk_add_f32 v[40:41], v[88:89], 1.0 op_sel_hi:[1,0] neg_lo:[1,0] neg_hi:[1,0]
	s_nop 0
	v_pk_mul_f32 v[40:41], v[40:41], v[90:91]
	s_nop 0
	v_cvt_pk_bf16_f32 v85, v40, v41
	v_sub_f32_e32 v41, v38, v39
	v_mul_f32_e32 v41, 0x3fb8aa3b, v41
	v_add_f32_e32 v39, v39, v81
	v_mul_f32_e32 v40, 0x3fb8aa3b, v82
	v_exp_f32_e32 v82, v41
	v_mul_f32_e32 v41, 0x3fb8aa3b, v81
	v_sub_f32_e32 v81, v38, v39
	v_mul_f32_e32 v81, 0x3fb8aa3b, v81
	v_add_f32_e32 v39, v39, v80
	v_exp_f32_e32 v83, v81
	v_sub_f32_e32 v81, v38, v39
	v_exp_f32_e32 v40, v40
	v_exp_f32_e32 v41, v41
	v_mul_f32_e32 v81, 0x3fb8aa3b, v81
	v_add_f32_e32 v39, v39, v79
	v_mul_f32_e32 v79, 0x3fb8aa3b, v79
	v_mul_f32_e32 v80, 0x3fb8aa3b, v80
	v_exp_f32_e32 v88, v81
	v_exp_f32_e32 v81, v79
	v_sub_f32_e32 v79, v38, v39
	v_exp_f32_e32 v80, v80
	v_mul_f32_e32 v79, 0x3fb8aa3b, v79
	v_exp_f32_e32 v89, v79
	v_pk_add_f32 v[40:41], v[40:41], 1.0 op_sel_hi:[1,0] neg_lo:[1,0] neg_hi:[1,0]
	v_add_f32_e32 v39, v39, v78
	v_pk_mul_f32 v[40:41], v[40:41], v[82:83]
	s_nop 0
	v_cvt_pk_bf16_f32 v86, v40, v41
	v_pk_add_f32 v[40:41], v[80:81], 1.0 op_sel_hi:[1,0] neg_lo:[1,0] neg_hi:[1,0]
	s_nop 0
	v_pk_mul_f32 v[40:41], v[40:41], v[88:89]
	s_nop 0
	v_cvt_pk_bf16_f32 v87, v40, v41
	v_sub_f32_e32 v41, v38, v39
	v_mul_f32_e32 v41, 0x3fb8aa3b, v41
	v_add_f32_e32 v39, v39, v77
	v_mul_f32_e32 v40, 0x3fb8aa3b, v78
	v_exp_f32_e32 v78, v41
	v_mul_f32_e32 v41, 0x3fb8aa3b, v77
	v_sub_f32_e32 v77, v38, v39
	v_add_f32_e32 v39, v39, v76
	v_mul_f32_e32 v76, 0x3fb8aa3b, v76
	v_exp_f32_e32 v40, v40
	v_exp_f32_e32 v41, v41
	v_mul_f32_e32 v77, 0x3fb8aa3b, v77
	v_exp_f32_e32 v80, v76
	v_sub_f32_e32 v76, v38, v39
	v_add_f32_e32 v39, v39, v75
	v_mul_f32_e32 v75, 0x3fb8aa3b, v75
	v_exp_f32_e32 v79, v77
	v_exp_f32_e32 v81, v75
	v_sub_f32_e32 v75, v38, v39
	v_mul_f32_e32 v76, 0x3fb8aa3b, v76
	v_mul_f32_e32 v75, 0x3fb8aa3b, v75
	v_exp_f32_e32 v82, v76
	v_exp_f32_e32 v83, v75
	v_pk_add_f32 v[40:41], v[40:41], 1.0 op_sel_hi:[1,0] neg_lo:[1,0] neg_hi:[1,0]
	v_add_f32_e32 v39, v39, v74
	v_pk_mul_f32 v[40:41], v[40:41], v[78:79]
	ds_write_b128 v53, v[84:87] offset:2624
	v_cvt_pk_bf16_f32 v76, v40, v41
	v_pk_add_f32 v[40:41], v[80:81], 1.0 op_sel_hi:[1,0] neg_lo:[1,0] neg_hi:[1,0]
	s_nop 0
	v_pk_mul_f32 v[40:41], v[40:41], v[82:83]
	s_nop 0
	v_cvt_pk_bf16_f32 v77, v40, v41
	v_sub_f32_e32 v41, v38, v39
	v_mul_f32_e32 v41, 0x3fb8aa3b, v41
	v_add_f32_e32 v39, v39, v73
	v_mul_f32_e32 v40, 0x3fb8aa3b, v74
	v_exp_f32_e32 v74, v41
	v_mul_f32_e32 v41, 0x3fb8aa3b, v73
	v_sub_f32_e32 v73, v38, v39
	v_mul_f32_e32 v73, 0x3fb8aa3b, v73
	v_add_f32_e32 v39, v39, v72
	v_exp_f32_e32 v75, v73
	v_sub_f32_e32 v73, v38, v39
	v_exp_f32_e32 v40, v40
	v_exp_f32_e32 v41, v41
	v_mul_f32_e32 v73, 0x3fb8aa3b, v73
	v_add_f32_e32 v39, v39, v71
	v_mul_f32_e32 v71, 0x3fb8aa3b, v71
	v_mul_f32_e32 v72, 0x3fb8aa3b, v72
	v_exp_f32_e32 v80, v73
	v_exp_f32_e32 v73, v71
	v_sub_f32_e32 v71, v38, v39
	v_exp_f32_e32 v72, v72
	v_mul_f32_e32 v71, 0x3fb8aa3b, v71
	v_exp_f32_e32 v81, v71
	v_pk_add_f32 v[40:41], v[40:41], 1.0 op_sel_hi:[1,0] neg_lo:[1,0] neg_hi:[1,0]
	v_add_f32_e32 v39, v39, v70
	v_pk_mul_f32 v[40:41], v[40:41], v[74:75]
	s_nop 0
	v_cvt_pk_bf16_f32 v78, v40, v41
	v_pk_add_f32 v[40:41], v[72:73], 1.0 op_sel_hi:[1,0] neg_lo:[1,0] neg_hi:[1,0]
	s_nop 0
; #define LAS __attribute__((address_space(3)))
; __device__ __forceinline__ unsigned pk2(float lo, float hi) { return pg8::cvt_pk_bf16(lo, hi); }
; #define LBAR() do { asm volatile("s_waitcnt lgkmcnt(0)" ::: "memory"); __builtin_amdgcn_s_barrier(); asm volatile("" ::: "memory"); } while (0)
; __device__ __forceinline__ void hg_a2_quad(unsigned char* ws, float* Gp, LAS unsigned char* lds, int quad, int tid) {
;     ...
; #pragma unroll
;         for (int i8 = 0; i8 < 8; ++i8) { unsigned kp[4];
; #pragma unroll
;             for (int j = 0; j < 4; ++j) { const float l0 = lf[8 * i8 + 2 * j], l1 = lf[8 * i8 + 2 * j + 1]; run += l0; const float a0 = (1.f - __expf(l0)) * __expf(blast - run); run += l1; const float a1 = (1.f - __expf(l1)) * __expf(blast - run); kp[j] = pk2(a0, a1); }
;             *(LAS v4u*)(KPt + k * GP + seg * 64 + 8 * i8) = (v4u){kp[0], kp[1], kp[2], kp[3]}; }
;         if (seg == 0) { const float e = __expf(blast); ((float*)(ws + WS_DEC))[unit * 128 + k] = e; dl[k] = e; }
;         LBAR();
	v_pk_mul_f32 v[40:41], v[40:41], v[80:81]
	s_nop 0
	v_cvt_pk_bf16_f32 v79, v40, v41
	v_sub_f32_e32 v41, v38, v39
	v_mul_f32_e32 v41, 0x3fb8aa3b, v41
	v_add_f32_e32 v39, v39, v69
	v_mul_f32_e32 v40, 0x3fb8aa3b, v70
	v_exp_f32_e32 v70, v41
	v_mul_f32_e32 v41, 0x3fb8aa3b, v69
	v_sub_f32_e32 v69, v38, v39
	v_add_f32_e32 v39, v39, v68
	v_mul_f32_e32 v68, 0x3fb8aa3b, v68
	v_exp_f32_e32 v40, v40
	v_exp_f32_e32 v41, v41
	v_mul_f32_e32 v69, 0x3fb8aa3b, v69
	v_exp_f32_e32 v72, v68
	v_sub_f32_e32 v68, v38, v39
	v_add_f32_e32 v39, v39, v67
	v_mul_f32_e32 v67, 0x3fb8aa3b, v67
	v_exp_f32_e32 v71, v69
	v_exp_f32_e32 v73, v67
	v_sub_f32_e32 v67, v38, v39
	v_mul_f32_e32 v68, 0x3fb8aa3b, v68
	v_mul_f32_e32 v67, 0x3fb8aa3b, v67
	v_exp_f32_e32 v74, v68
	v_exp_f32_e32 v75, v67
	v_pk_add_f32 v[40:41], v[40:41], 1.0 op_sel_hi:[1,0] neg_lo:[1,0] neg_hi:[1,0]
	v_add_f32_e32 v39, v39, v66
	v_pk_mul_f32 v[40:41], v[40:41], v[70:71]
	ds_write_b128 v53, v[76:79] offset:2640
	v_cvt_pk_bf16_f32 v68, v40, v41
	v_pk_add_f32 v[40:41], v[72:73], 1.0 op_sel_hi:[1,0] neg_lo:[1,0] neg_hi:[1,0]
	s_nop 0
	v_pk_mul_f32 v[40:41], v[40:41], v[74:75]
	s_nop 0
	v_cvt_pk_bf16_f32 v69, v40, v41
	v_sub_f32_e32 v41, v38, v39
	v_mul_f32_e32 v41, 0x3fb8aa3b, v41
	v_add_f32_e32 v39, v39, v65
	v_mul_f32_e32 v40, 0x3fb8aa3b, v66
	v_exp_f32_e32 v66, v41
	v_mul_f32_e32 v41, 0x3fb8aa3b, v65
	v_sub_f32_e32 v65, v38, v39
	v_mul_f32_e32 v65, 0x3fb8aa3b, v65
	v_add_f32_e32 v39, v39, v64
	v_exp_f32_e32 v67, v65
	v_sub_f32_e32 v65, v38, v39
	v_exp_f32_e32 v40, v40
	v_exp_f32_e32 v41, v41
	v_mul_f32_e32 v65, 0x3fb8aa3b, v65
	v_add_f32_e32 v39, v39, v63
	v_mul_f32_e32 v63, 0x3fb8aa3b, v63
	v_mul_f32_e32 v64, 0x3fb8aa3b, v64
	v_exp_f32_e32 v72, v65
	v_exp_f32_e32 v65, v63
	v_sub_f32_e32 v63, v38, v39
	v_exp_f32_e32 v64, v64
	v_mul_f32_e32 v63, 0x3fb8aa3b, v63
	v_exp_f32_e32 v73, v63
	v_pk_add_f32 v[40:41], v[40:41], 1.0 op_sel_hi:[1,0] neg_lo:[1,0] neg_hi:[1,0]
	v_add_f32_e32 v39, v39, v62
	v_pk_mul_f32 v[40:41], v[40:41], v[66:67]
	s_nop 0
	v_cvt_pk_bf16_f32 v70, v40, v41
	v_pk_add_f32 v[40:41], v[64:65], 1.0 op_sel_hi:[1,0] neg_lo:[1,0] neg_hi:[1,0]
	s_nop 0
	v_pk_mul_f32 v[40:41], v[40:41], v[72:73]
	s_nop 0
	v_cvt_pk_bf16_f32 v71, v40, v41
	v_sub_f32_e32 v41, v38, v39
	v_mul_f32_e32 v41, 0x3fb8aa3b, v41
	v_add_f32_e32 v39, v39, v61
	v_mul_f32_e32 v40, 0x3fb8aa3b, v62
	v_exp_f32_e32 v62, v41
	v_mul_f32_e32 v41, 0x3fb8aa3b, v61
	v_sub_f32_e32 v61, v38, v39
	v_add_f32_e32 v39, v39, v60
	v_mul_f32_e32 v60, 0x3fb8aa3b, v60
	v_exp_f32_e32 v40, v40
	v_exp_f32_e32 v41, v41
	v_mul_f32_e32 v61, 0x3fb8aa3b, v61
	v_exp_f32_e32 v64, v60
	v_sub_f32_e32 v60, v38, v39
	v_add_f32_e32 v39, v39, v59
	v_mul_f32_e32 v59, 0x3fb8aa3b, v59
	v_exp_f32_e32 v63, v61
	v_exp_f32_e32 v65, v59
	v_sub_f32_e32 v59, v38, v39
	v_mul_f32_e32 v60, 0x3fb8aa3b, v60
	v_mul_f32_e32 v59, 0x3fb8aa3b, v59
	v_exp_f32_e32 v66, v60
	v_exp_f32_e32 v67, v59
	v_pk_add_f32 v[40:41], v[40:41], 1.0 op_sel_hi:[1,0] neg_lo:[1,0] neg_hi:[1,0]
	v_add_f32_e32 v39, v39, v58
	v_pk_mul_f32 v[40:41], v[40:41], v[62:63]
	ds_write_b128 v53, v[68:71] offset:2656
	v_cvt_pk_bf16_f32 v60, v40, v41
	v_pk_add_f32 v[40:41], v[64:65], 1.0 op_sel_hi:[1,0] neg_lo:[1,0] neg_hi:[1,0]
	s_nop 0
	v_pk_mul_f32 v[40:41], v[40:41], v[66:67]
	s_nop 0
	v_cvt_pk_bf16_f32 v61, v40, v41
	v_sub_f32_e32 v41, v38, v39
	v_mul_f32_e32 v41, 0x3fb8aa3b, v41
	v_add_f32_e32 v39, v39, v57
	v_mul_f32_e32 v40, 0x3fb8aa3b, v58
	v_exp_f32_e32 v58, v41
	v_mul_f32_e32 v41, 0x3fb8aa3b, v57
	v_sub_f32_e32 v57, v38, v39
	v_mul_f32_e32 v57, 0x3fb8aa3b, v57
	v_add_f32_e32 v39, v39, v56
	v_exp_f32_e32 v59, v57
	v_sub_f32_e32 v57, v38, v39
	v_exp_f32_e32 v40, v40
	v_exp_f32_e32 v41, v41
	v_mul_f32_e32 v57, 0x3fb8aa3b, v57
	v_add_f32_e32 v39, v39, v37
	v_mul_f32_e32 v37, 0x3fb8aa3b, v37
	v_mul_f32_e32 v56, 0x3fb8aa3b, v56
	v_exp_f32_e32 v64, v57
	v_exp_f32_e32 v57, v37
	v_sub_f32_e32 v37, v38, v39
	v_exp_f32_e32 v56, v56
	v_mul_f32_e32 v37, 0x3fb8aa3b, v37
	v_exp_f32_e32 v65, v37
	v_pk_add_f32 v[40:41], v[40:41], 1.0 op_sel_hi:[1,0] neg_lo:[1,0] neg_hi:[1,0]
	s_nop 0
	v_pk_mul_f32 v[40:41], v[40:41], v[58:59]
	s_nop 0
	v_cvt_pk_bf16_f32 v62, v40, v41
	v_pk_add_f32 v[40:41], v[56:57], 1.0 op_sel_hi:[1,0] neg_lo:[1,0] neg_hi:[1,0]
	s_nop 0
	v_pk_mul_f32 v[40:41], v[40:41], v[64:65]
	s_nop 0
	v_cvt_pk_bf16_f32 v63, v40, v41
	ds_write_b128 v53, v[60:63] offset:2672
	s_and_saveexec_b64 s[22:23], s[4:5]
	s_cbranch_execz .LBB0_578
	v_mul_f32_e32 v37, 0x3fb8aa3b, v38
	v_exp_f32_e32 v40, v37
	v_ashrrev_i32_e32 v37, 31, v36
	v_lshl_add_u64 v[38:39], v[36:37], 2, s[18:19]
	global_store_dword v[38:39], v40, off sc1
	ds_write_b32 v49, v40 offset:2048
	s_branch .LBB0_578

; #define LAS __attribute__((address_space(3)))
; #define SEAM(k) do { if (IN(k) && IN((k) + 1)) flat_barrier((unsigned*)(ws + WS_BAR + 65536), fgen, (unsigned)G); } while (0)
; #define SEAM(k) do { if (IN(k) && IN((k) + 1)) xcd_barrier(xbar); } while (0)
; __global__ void __launch_bounds__(NT, 2) hymba_fwd(Args args) {
;     ...
;         const int GA = (G * 3) / 4;
;         if (bx < GA) {
;             pg8::Gemm g{XB, (const bf16*)(ws + WS_WIN) + (size_t)2048 * D, M, 1536, D}; pg8::StaticOrder S; S.init(M, 1536, GA, bx);
;             pg8::EpiWin E{(bf16*)(ws + WS_QS), (bf16*)(ws + WS_VV), (bf16*)(ws + WS_GS), (bf16*)(ws + WS_BC), (bf16*)(ws + WS_CU), (_Float16*)(ws + WS_LF), ssq + M, args.in[I_LB], 8};
;             pg8::gemm_phase<pg8::EpiWin, pg8::StaticOrder, true, true>(lds, g, S, E);
;         } else {
;             for (int qd = bx - GA; qd < 64; qd += G - GA) hg_a2_quad(ws, args.out, lds, qd, tid);
;         }
;     }
;     if (IN(4)) p0_items(args, (LAS float*)(lds + wave * 16384), P0_MID, P0_GU2, gw, NGW, lane);
;     SEAM(4);
.Lgb4_wait:
	s_mov_b32 s101, s17
	s_mul_i32 s14, s3, 3
	s_lshr_b32 s14, s14, 2
	s_sub_i32 s18, s3, s14
	s_cmp_lt_u32 s2, s14
	s_cbranch_scc1 .Lgb4_hgw
	v_mov_b32_e32 v0, 0x8900
	global_atomic_add v0, v1, s[46:47]

; #define LAS __attribute__((address_space(3)))
; #define SEAM(k) do { if (IN(k) && IN((k) + 1)) flat_barrier((unsigned*)(ws + WS_BAR + 65536), fgen, (unsigned)G); } while (0)
; #define SEAM(k) do { if (IN(k) && IN((k) + 1)) xcd_barrier(xbar); } while (0)
; __global__ void __launch_bounds__(NT, 2) hymba_fwd(Args args) {
;     ...
;     if (IN(4)) p0_items(args, (LAS float*)(lds + wave * 16384), P0_MID, P0_GU2, gw, NGW, lane);
;     SEAM(4);
;     if (IN(5)) _Pragma("unroll") for (int rep = 0; rep < NREP(5); ++rep) {
;         if (M % (4 * NGW) == 0) { for (int r = gw; r < M; r += 4 * NGW) conv_rows<4>(args, r, NGW, lane); } else { for (int r = gw; r < M; r += NGW) conv_rows<1>(args, r, NGW, lane); }
;         for (int u = vcu; u < 256; u += G) hg_c2_unit(args, args.out, lds, u, tid);
;     }
;     SEAM(5);
.Lgb4_hgpoll:
	global_load_dword v4, v0, s[46:47] sc1
	s_waitcnt vmcnt(0)
	v_readfirstlane_b32 s14, v4
	s_cmp_ge_u32 s14, s18
	s_cbranch_scc1 .Lgb4_acq
	s_sleep 1
	s_add_i32 s19, s19, 1
	s_cmp_lt_u32 s19, 20000
	s_cbranch_scc1 .Lgb4_hgpoll

; template <int NR>
; __device__ __forceinline__ void conv_rows(const Args& a, int r0, int rstride, int lane) {
;     unsigned char* ws = a.ws; const int c0 = 8 * lane;
;     const bf16* BCp = (const bf16*)(ws + WS_BC); const bf16* CUp = (const bf16*)(ws + WS_CU);
;     v4u bq[NR], u0[NR], u1[NR], u2[NR];
; #pragma unroll
;     for (int i = 0; i < NR; ++i) { const int row = r0 + i * rstride, t = row & (SEQ - 1);
;         bq[i] = *(const v4u*)(BCp + (size_t)row * 512 + c0); u0[i] = *(const v4u*)(CUp + (size_t)row * 512 + c0);
;         u1[i] = (v4u){0, 0, 0, 0}; u2[i] = (v4u){0, 0, 0, 0};
;         if (t >= 1) u1[i] = *(const v4u*)(CUp + (size_t)(row - 1) * 512 + c0);
;         if (t >= 2) u2[i] = *(const v4u*)(CUp + (size_t)(row - 2) * 512 + c0); }
;     const float* cw = a.in[I_CONVW] + c0; const float* gn = a.in[I_CONVN] + c0;
;     const f32x4 w0a = *(const f32x4*)(cw), w0b = *(const f32x4*)(cw + 4), w1a = *(const f32x4*)(cw + 512), w1b = *(const f32x4*)(cw + 516), w2a = *(const f32x4*)(cw + 1024), w2b = *(const f32x4*)(cw + 1028);
; __global__ void __launch_bounds__(NT, 2) hymba_fwd(Args args) {
;     ...
;     if (IN(5)) _Pragma("unroll") for (int rep = 0; rep < NREP(5); ++rep) {
;         if (M % (4 * NGW) == 0) { for (int r = gw; r < M; r += 4 * NGW) conv_rows<4>(args, r, NGW, lane); } else { for (int r = gw; r < M; r += NGW) conv_rows<1>(args, r, NGW, lane); }
;         for (int u = vcu; u < 256; u += G) hg_c2_unit(args, args.out, lds, u, tid);
.LBB0_743:
	s_cmp_lt_i32 s50, 6
	s_cselect_b64 s[6:7], -1, 0
	s_and_b64 s[62:63], s[6:7], s[4:5]
	s_andn2_b64 vcc, exec, s[62:63]
	s_cbranch_vccnz .LBB0_939
	s_mov_b32 s98, s24
	s_load_dwordx4 s[16:19], s[0:1], 0xa8
	s_load_dwordx4 s[12:15], s[0:1], 0x40
	v_lshlrev_b32_e32 v96, 4, v208
	v_mov_b32_e32 v97, 0
	s_waitcnt vmcnt(0) lgkmcnt(0)
	s_branch .LBB0_776
.Lp5_conv:
	s_mov_b32 s24, s98
	s_cmp_eq_u32 s101, 0
	s_cbranch_scc1 .Lp5_sync
	s_mov_b64 exec, 1
	s_lshl_b32 s72, s33, 8
	s_add_u32 s72, s46, s72
	s_addc_u32 s73, s47, 0
	v_mov_b32_e32 v0, 0x10000
	s_mov_b32 s99, 0
.Lp5_poll:
	global_load_dword v1, v0, s[72:73] sc1
	s_waitcnt vmcnt(0)
	v_readfirstlane_b32 s74, v1
	s_cmp_ge_u32 s74, s101
	s_cbranch_scc1 .Lp5_acq
	s_sleep 1
	s_add_i32 s99, s99, 1
	s_cmp_lt_u32 s99, 20000
	s_cbranch_scc1 .Lp5_poll
.Lp5_acq:
	buffer_inv sc1
	s_waitcnt vmcnt(0)
	s_mov_b32 s101, 0
	s_mov_b64 exec, -1
.Lp5_sync:
	s_waitcnt vmcnt(0) lgkmcnt(0)
	s_barrier
	s_lshl_b32 s4, s3, 5
	s_abs_i32 s6, s4
	s_waitcnt vmcnt(0)
	v_cvt_f32_u32_e32 v0, s6
	s_sub_i32 s7, 0, s6
	s_load_dwordx4 s[16:19], s[0:1], 0xa8
	v_mov_b32_e32 v97, 0
	v_rcp_iflag_f32_e32 v0, v0
	v_lshlrev_b32_e32 v96, 4, v208
	s_mov_b64 s[4:5], 0xb000000
	v_mul_f32_e32 v0, 0x4f7ffffe, v0
	v_cvt_u32_f32_e32 v2, v0
	s_waitcnt lgkmcnt(0)
	v_lshl_add_u64 v[0:1], s[18:19], 0, v[96:97]
	v_lshl_add_u64 v[98:99], v[0:1], 0, s[4:5]
	v_lshlrev_b32_e32 v0, 5, v208
	v_readfirstlane_b32 s8, v2
	s_mul_i32 s7, s7, s8
	s_mul_hi_u32 s7, s8, s7
	s_add_i32 s8, s8, s7
	s_lshr_b32 s7, s8, 18
	s_mul_i32 s7, s7, s6
	s_sub_i32 s7, 0x4000, s7
	s_sub_i32 s8, s7, s6
	s_cmp_ge_u32 s7, s6
	s_cselect_b32 s7, s8, s7
	s_sub_i32 s8, s7, s6
	s_cmp_ge_u32 s7, s6
	s_cselect_b32 s8, s8, s7
	s_cmpk_lt_i32 s24, 0x4000
	s_cselect_b64 s[6:7], -1, 0
	s_cmp_eq_u32 s8, 0
	s_load_dwordx4 s[12:15], s[0:1], 0x40
	s_load_dwordx2 s[8:9], s[0:1], 0x50
	v_mov_b32_e32 v1, v97
	s_mov_b64 s[4:5], 0x1000
	s_waitcnt lgkmcnt(0)
	v_lshl_add_u64 v[100:101], s[14:15], 0, v[0:1]
	v_lshl_add_u64 v[102:103], s[8:9], 0, v[0:1]
	v_cndmask_b32_e64 v0, 0, 1, s[6:7]
	v_lshl_add_u64 v[104:105], v[100:101], 0, s[4:5]
	v_cmp_ne_u32_e64 s[4:5], 1, v0
	s_cbranch_scc1 .LBB0_754
	s_and_b64 vcc, exec, s[4:5]
	s_cbranch_vccnz .LBB0_753
	v_mbcnt_lo_u32_b32 v0, -1, 0
	v_mbcnt_hi_u32_b32 v0, -1, v0
	v_and_b32_e32 v2, 64, v0
	v_xor_b32_e32 v1, 32, v0
	v_add_u32_e32 v2, 64, v2
	v_cmp_lt_i32_e32 vcc, v1, v2
	s_ashr_i32 s25, s24, 31
	s_lshl_b64 s[6:7], s[24:25], 11
	v_cndmask_b32_e32 v1, v0, v1, vcc
	v_lshlrev_b32_e32 v12, 2, v1
	v_xor_b32_e32 v1, 16, v0
	v_cmp_lt_i32_e32 vcc, v1, v2
	s_add_u32 s6, s18, s6
	v_mov_b32_e32 v97, 0
	v_cndmask_b32_e32 v1, v0, v1, vcc
	v_lshlrev_b32_e32 v13, 2, v1
	v_xor_b32_e32 v1, 8, v0
	v_cmp_lt_i32_e32 vcc, v1, v2
	s_addc_u32 s7, s19, s7
	s_ashr_i32 s59, s58, 31
	v_cndmask_b32_e32 v1, v0, v1, vcc
	v_lshlrev_b32_e32 v14, 2, v1
	v_xor_b32_e32 v1, 4, v0
	v_cmp_lt_i32_e32 vcc, v1, v2
	s_lshl_b64 s[8:9], s[24:25], 10
	v_mov_b32_e32 v18, 0x358637bd
	v_cndmask_b32_e32 v1, v0, v1, vcc
	v_lshlrev_b32_e32 v15, 2, v1
	v_xor_b32_e32 v1, 2, v0
	v_cmp_lt_i32_e32 vcc, v1, v2
	s_mov_b32 s10, 0x800000
	s_mov_b32 s11, s24
	v_cndmask_b32_e32 v1, v0, v1, vcc
	v_lshlrev_b32_e32 v16, 2, v1
	v_xor_b32_e32 v1, 1, v0
	v_cmp_lt_i32_e32 vcc, v1, v2
	s_nop 1
	v_cndmask_b32_e32 v0, v0, v1, vcc
	v_lshlrev_b32_e32 v17, 2, v0
	v_lshl_add_u64 v[0:1], s[6:7], 0, v[96:97]
	s_mov_b64 s[6:7], 0xe000400
	v_lshl_add_u64 v[8:9], v[0:1], 0, s[6:7]
	s_lshl_b64 s[6:7], s[58:59], 11
	s_add_u32 s8, s18, s8
	s_addc_u32 s9, s19, s9
	v_lshl_add_u64 v[0:1], s[8:9], 0, v[96:97]
	s_mov_b64 s[8:9], 0xa000000
	v_lshl_add_u64 v[10:11], v[0:1], 0, s[8:9]
	s_lshl_b64 s[8:9], s[58:59], 10
	s_branch .LBB0_748

; __global__ void __launch_bounds__(NT, 2) hymba_fwd(Args args) {
;     ...
;     if (IN(5)) _Pragma("unroll") for (int rep = 0; rep < NREP(5); ++rep) {
;         if (M % (4 * NGW) == 0) { for (int r = gw; r < M; r += 4 * NGW) conv_rows<4>(args, r, NGW, lane); } else { for (int r = gw; r < M; r += NGW) conv_rows<1>(args, r, NGW, lane); }
;         for (int u = vcu; u < 256; u += G) hg_c2_unit(args, args.out, lds, u, tid);
.LBB0_938:
	s_mov_b32 s88, s52
	s_branch .Lp5_conv
